# layer-0 P2 conversion slot shared: WGs >= 128 two tiles per wave, WGs < 128 one tile per wave (was three per wave on WGs >= 128 only)
# speedup vs baseline: 1.0026x; 1.0026x over previous
.LBB0_441:
	s_or_b64 exec, exec, s[40:41]
	s_xor_b64 s[0:1], s[62:63], -1
	v_writelane_b32 v252, s0, 48
	s_mov_b32 s37, s93
	s_andn2_b64 vcc, exec, s[66:67]
	v_writelane_b32 v252, s1, 49
	s_waitcnt lgkmcnt(0)
	s_barrier
	s_cbranch_vccnz .LBB0_531
	v_readlane_b32 s98, v252, 47
	s_cmp_lg_u32 s98, 0
	s_cbranch_scc1 .Lw1b_skip
	s_cmpk_lg_u32 s78, 0x100
	s_cbranch_scc1 .Lw1b_skip
	s_cmpk_lt_u32 s2, 0x80
	s_cbranch_scc1 .Lw1b_skip
	v_writelane_b32 v254, s8, 0
	v_writelane_b32 v254, s9, 1
	v_writelane_b32 v254, s10, 2
	v_writelane_b32 v254, s11, 3
	v_writelane_b32 v254, s12, 4
	v_writelane_b32 v254, s13, 5
	v_writelane_b32 v254, s14, 6
	v_writelane_b32 v254, s15, 7
	v_writelane_b32 v254, s16, 8
	v_writelane_b32 v254, s17, 9
	v_writelane_b32 v254, s18, 10
	v_writelane_b32 v254, s19, 11
	v_writelane_b32 v254, s20, 12
	v_writelane_b32 v254, s21, 13
	v_writelane_b32 v254, s22, 14
	v_writelane_b32 v254, s23, 15
	v_writelane_b32 v254, s24, 16
	v_writelane_b32 v254, s25, 17
	v_writelane_b32 v254, s26, 18
	v_writelane_b32 v254, s27, 19
	v_writelane_b32 v254, s28, 20
	v_writelane_b32 v254, s29, 21
	v_writelane_b32 v254, s30, 22
	v_writelane_b32 v254, s31, 23
	v_writelane_b32 v254, s32, 24
	v_writelane_b32 v254, s33, 25
	v_writelane_b32 v254, s34, 26
	v_writelane_b32 v254, s35, 27
	v_writelane_b32 v254, s40, 28
	v_writelane_b32 v254, s41, 29
	v_writelane_b32 v254, s42, 30
	v_writelane_b32 v254, s43, 31
	v_writelane_b32 v254, s44, 32
	v_writelane_b32 v254, s45, 33
	v_writelane_b32 v254, s46, 34
	v_writelane_b32 v254, s47, 35
	v_writelane_b32 v254, s48, 36
	v_writelane_b32 v254, s49, 37
	v_writelane_b32 v254, s50, 38
	v_writelane_b32 v254, s51, 39
	v_writelane_b32 v254, s52, 40
	v_writelane_b32 v254, s53, 41
	v_writelane_b32 v254, s54, 42
	v_writelane_b32 v254, s55, 43
	v_writelane_b32 v254, s56, 44
	v_writelane_b32 v254, s57, 45
	v_writelane_b32 v254, s58, 46
	v_writelane_b32 v254, s59, 47
	v_writelane_b32 v254, s60, 48
	v_writelane_b32 v254, s61, 49
	v_writelane_b32 v254, s62, 50
	v_writelane_b32 v254, s63, 51
	v_writelane_b32 v254, s66, 52
	v_writelane_b32 v254, s67, 53
	v_writelane_b32 v254, s68, 54
	v_writelane_b32 v254, s69, 55
	v_writelane_b32 v254, s70, 56
	v_writelane_b32 v254, s71, 57
	v_writelane_b32 v254, s72, 58
	v_writelane_b32 v254, s73, 59
	v_writelane_b32 v254, s74, 60
	v_writelane_b32 v254, s75, 61
	v_writelane_b32 v254, s76, 62
	v_writelane_b32 v254, s77, 63
	v_writelane_b32 v255, s80, 0
	v_writelane_b32 v255, s81, 1
	v_writelane_b32 v255, s82, 2
	v_writelane_b32 v255, s83, 3
	v_writelane_b32 v255, s84, 4
	v_writelane_b32 v255, s85, 5
	v_writelane_b32 v255, s86, 6
	v_writelane_b32 v255, s87, 7
	v_writelane_b32 v255, s88, 8
	v_writelane_b32 v255, s89, 9
	v_writelane_b32 v255, s90, 10
	v_writelane_b32 v255, s91, 11
	v_writelane_b32 v255, s92, 12
	v_writelane_b32 v255, s93, 13
	v_writelane_b32 v255, s94, 14
	v_writelane_b32 v255, s95, 15
	v_writelane_b32 v255, s4, 16
	v_writelane_b32 v255, s5, 17
	v_writelane_b32 v255, s0, 18
	v_writelane_b32 v255, s1, 19
	v_and_b32_e32 v207, 31, v227
	v_lshlrev_b32_e32 v200, 4, v207
	v_lshrrev_b32_e32 v201, 5, v227
	v_lshlrev_b32_e32 v202, 2, v207
	v_and_b32_e32 v203, 64, v202
	v_add_u32_e32 v203, v203, v202
	v_lshlrev_b32_e32 v204, 5, v201
	v_readlane_b32 s8, v253, 36
	v_readlane_b32 s9, v253, 37
	v_readlane_b32 s10, v253, 34
	v_readlane_b32 s11, v253, 35
	v_readlane_b32 s12, v253, 16
	v_readlane_b32 s13, v253, 17
	v_readlane_b32 s14, v253, 18
	v_readlane_b32 s15, v253, 19
	v_readlane_b32 s16, v253, 20
	v_readlane_b32 s17, v253, 21
	v_readlane_b32 s18, v253, 22
	v_readlane_b32 s19, v253, 23
	v_readfirstlane_b32 s66, v226
	s_lshr_b32 s66, s66, 6
	s_add_i32 s67, s2, 0xffffff80
	s_lshl_b32 s67, s67, 3
	s_add_i32 s66, s66, s67
	s_addk_i32 s66, 0x400
	s_add_i32 s68, s66, 0x400
	s_cmpk_ge_i32 s66, 0xc00
	s_cselect_b32 s0, 1, 0
	s_mul_i32 s1, s0, 0xc00
	s_sub_i32 s1, s66, s1
	s_mul_i32 s4, s0, 0x1800000
	s_add_u32 s70, s64, s4
	s_addc_u32 s71, s65, 0
	s_lshl_b32 s69, s0, 12
	s_cmpk_lt_i32 s1, 0x300
	s_cbranch_scc1 .Lw1b_in_17
	s_cmpk_lt_i32 s1, 0x400
	s_cbranch_scc1 .Lw1b_out_17
	s_cmpk_lt_i32 s1, 0x800
	s_cbranch_scc1 .Lw1b_up_17
	s_sub_i32 s1, s1, 0x800
	s_and_b32 s75, s1, 1
	s_lshr_b32 s1, s1, 1
	s_lshr_b32 s72, s1, 3
	s_and_b32 s73, s1, 7
	s_lshl_b32 s72, s72, 1
	s_or_b32 s72, s72, s75
	s_movk_i32 s74, 0x400
	s_mul_i32 s4, s0, 0x1000000
	s_add_u32 s76, s18, s4
	s_addc_u32 s77, s19, 0
	s_mov_b32 s4, 0x1000000
	s_lshl_b32 s5, s73, 7
	s_movk_i32 s27, 0xd00
	s_branch .Lw1b_join_17

.Lw1b_skip:
	v_readlane_b32 s98, v252, 47
	s_cmp_lg_u32 s98, 0
	s_cbranch_scc1 .Lw1d_skip
	s_cmpk_lg_u32 s78, 0x100
	s_cbranch_scc1 .Lw1d_skip
	s_cmpk_gt_u32 s2, 0x7f
	s_cbranch_scc1 .Lw1d_skip
	v_writelane_b32 v254, s8, 0
	v_writelane_b32 v254, s9, 1
	v_writelane_b32 v254, s10, 2
	v_writelane_b32 v254, s11, 3
	v_writelane_b32 v254, s12, 4
	v_writelane_b32 v254, s13, 5
	v_writelane_b32 v254, s14, 6
	v_writelane_b32 v254, s15, 7
	v_writelane_b32 v254, s16, 8
	v_writelane_b32 v254, s17, 9
	v_writelane_b32 v254, s18, 10
	v_writelane_b32 v254, s19, 11
	v_writelane_b32 v254, s20, 12
	v_writelane_b32 v254, s21, 13
	v_writelane_b32 v254, s22, 14
	v_writelane_b32 v254, s23, 15
	v_writelane_b32 v254, s24, 16
	v_writelane_b32 v254, s25, 17
	v_writelane_b32 v254, s26, 18
	v_writelane_b32 v254, s27, 19
	v_writelane_b32 v254, s28, 20
	v_writelane_b32 v254, s29, 21
	v_writelane_b32 v254, s30, 22
	v_writelane_b32 v254, s31, 23
	v_writelane_b32 v254, s32, 24
	v_writelane_b32 v254, s33, 25
	v_writelane_b32 v254, s34, 26
	v_writelane_b32 v254, s35, 27
	v_writelane_b32 v254, s40, 28
	v_writelane_b32 v254, s41, 29
	v_writelane_b32 v254, s42, 30
	v_writelane_b32 v254, s43, 31
	v_writelane_b32 v254, s44, 32
	v_writelane_b32 v254, s45, 33
	v_writelane_b32 v254, s46, 34
	v_writelane_b32 v254, s47, 35
	v_writelane_b32 v254, s48, 36
	v_writelane_b32 v254, s49, 37
	v_writelane_b32 v254, s50, 38
	v_writelane_b32 v254, s51, 39
	v_writelane_b32 v254, s52, 40
	v_writelane_b32 v254, s53, 41
	v_writelane_b32 v254, s54, 42
	v_writelane_b32 v254, s55, 43
	v_writelane_b32 v254, s56, 44
	v_writelane_b32 v254, s57, 45
	v_writelane_b32 v254, s58, 46
	v_writelane_b32 v254, s59, 47
	v_writelane_b32 v254, s60, 48
	v_writelane_b32 v254, s61, 49
	v_writelane_b32 v254, s62, 50
	v_writelane_b32 v254, s63, 51
	v_writelane_b32 v254, s66, 52
	v_writelane_b32 v254, s67, 53
	v_writelane_b32 v254, s68, 54
	v_writelane_b32 v254, s69, 55
	v_writelane_b32 v254, s70, 56
	v_writelane_b32 v254, s71, 57
	v_writelane_b32 v254, s72, 58
	v_writelane_b32 v254, s73, 59
	v_writelane_b32 v254, s74, 60
	v_writelane_b32 v254, s75, 61
	v_writelane_b32 v254, s76, 62
	v_writelane_b32 v254, s77, 63
	v_writelane_b32 v255, s80, 0
	v_writelane_b32 v255, s81, 1
	v_writelane_b32 v255, s82, 2
	v_writelane_b32 v255, s83, 3
	v_writelane_b32 v255, s84, 4
	v_writelane_b32 v255, s85, 5
	v_writelane_b32 v255, s86, 6
	v_writelane_b32 v255, s87, 7
	v_writelane_b32 v255, s88, 8
	v_writelane_b32 v255, s89, 9
	v_writelane_b32 v255, s90, 10
	v_writelane_b32 v255, s91, 11
	v_writelane_b32 v255, s92, 12
	v_writelane_b32 v255, s93, 13
	v_writelane_b32 v255, s94, 14
	v_writelane_b32 v255, s95, 15
	v_writelane_b32 v255, s4, 16
	v_writelane_b32 v255, s5, 17
	v_writelane_b32 v255, s0, 18
	v_writelane_b32 v255, s1, 19
	v_and_b32_e32 v207, 31, v227
	v_lshlrev_b32_e32 v200, 4, v207
	v_lshrrev_b32_e32 v201, 5, v227
	v_lshlrev_b32_e32 v202, 2, v207
	v_and_b32_e32 v203, 64, v202
	v_add_u32_e32 v203, v203, v202
	v_lshlrev_b32_e32 v204, 5, v201
	v_readlane_b32 s8, v253, 36
	v_readlane_b32 s9, v253, 37
	v_readlane_b32 s10, v253, 34
	v_readlane_b32 s11, v253, 35
	v_readlane_b32 s12, v253, 16
	v_readlane_b32 s13, v253, 17
	v_readlane_b32 s14, v253, 18
	v_readlane_b32 s15, v253, 19
	v_readlane_b32 s16, v253, 20
	v_readlane_b32 s17, v253, 21
	v_readlane_b32 s18, v253, 22
	v_readlane_b32 s19, v253, 23
	v_readfirstlane_b32 s66, v226
	s_lshr_b32 s66, s66, 6
	s_lshl_b32 s67, s2, 3
	s_add_i32 s66, s66, s67
	s_addk_i32 s66, 0xc00
	s_add_i32 s68, s66, 0x400
	s_cmpk_ge_i32 s66, 0xc00
	s_cselect_b32 s0, 1, 0
	s_mul_i32 s1, s0, 0xc00
	s_sub_i32 s1, s66, s1
	s_mul_i32 s4, s0, 0x1800000
	s_add_u32 s70, s64, s4
	s_addc_u32 s71, s65, 0
	s_lshl_b32 s69, s0, 12
	s_cmpk_lt_i32 s1, 0x300
	s_cbranch_scc1 .Lw1d_in_21
	s_cmpk_lt_i32 s1, 0x400
	s_cbranch_scc1 .Lw1d_out_21
	s_cmpk_lt_i32 s1, 0x800
	s_cbranch_scc1 .Lw1d_up_21
	s_sub_i32 s1, s1, 0x800
	s_and_b32 s75, s1, 1
	s_lshr_b32 s1, s1, 1
	s_lshr_b32 s72, s1, 3
	s_and_b32 s73, s1, 7
	s_lshl_b32 s72, s72, 1
	s_or_b32 s72, s72, s75
	s_movk_i32 s74, 0x400
	s_mul_i32 s4, s0, 0x1000000
	s_add_u32 s76, s18, s4
	s_addc_u32 s77, s19, 0
	s_mov_b32 s4, 0x1000000
	s_lshl_b32 s5, s73, 7
	s_movk_i32 s27, 0xd00
	s_branch .Lw1d_join_21

.Lw1d_join_21:
	s_mul_i32 s0, s72, s74
	s_lshl_b32 s0, s0, 5
	s_lshl_b32 s1, s73, 7
	s_add_i32 s0, s0, s1
	s_lshl_b32 s0, s0, 2
	s_add_u32 s20, s76, s0
	s_addc_u32 s21, s77, 0
	s_lshl_b32 s26, s74, 2
	s_lshr_b32 s0, s27, 8
	s_lshl_b32 s0, s5, s0
	s_add_i32 s0, s0, s4
	s_lshl_b32 s1, s72, 6
	s_add_i32 s0, s0, s1
	s_add_u32 s22, s70, s0
	s_addc_u32 s23, s71, 0
	s_lshl_b32 s1, s72, 7
	s_add_u32 s24, s24, s1
	s_addc_u32 s25, s25, 0
	s_lshl_b32 s0, s26, 4
	v_mad_u32_u24 v205, v201, s0, v200
	global_load_dwordx4 v[8:11], v205, s[20:21] nt
	s_add_u32 s20, s20, s26
	s_addc_u32 s21, s21, 0
	global_load_dwordx4 v[12:15], v205, s[20:21] nt
	s_add_u32 s20, s20, s26
	s_addc_u32 s21, s21, 0
	global_load_dwordx4 v[16:19], v205, s[20:21] nt
	s_add_u32 s20, s20, s26
	s_addc_u32 s21, s21, 0
	global_load_dwordx4 v[20:23], v205, s[20:21] nt
	s_add_u32 s20, s20, s26
	s_addc_u32 s21, s21, 0
	global_load_dwordx4 v[24:27], v205, s[20:21] nt
	s_add_u32 s20, s20, s26
	s_addc_u32 s21, s21, 0
	global_load_dwordx4 v[28:31], v205, s[20:21] nt
	s_add_u32 s20, s20, s26
	s_addc_u32 s21, s21, 0
	global_load_dwordx4 v[32:35], v205, s[20:21] nt
	s_add_u32 s20, s20, s26
	s_addc_u32 s21, s21, 0
	global_load_dwordx4 v[36:39], v205, s[20:21] nt
	s_add_u32 s20, s20, s26
	s_addc_u32 s21, s21, 0
	global_load_dwordx4 v[40:43], v205, s[20:21] nt
	s_add_u32 s20, s20, s26
	s_addc_u32 s21, s21, 0
	global_load_dwordx4 v[44:47], v205, s[20:21] nt
	s_add_u32 s20, s20, s26
	s_addc_u32 s21, s21, 0
	global_load_dwordx4 v[48:51], v205, s[20:21] nt
	s_add_u32 s20, s20, s26
	s_addc_u32 s21, s21, 0
	global_load_dwordx4 v[52:55], v205, s[20:21] nt
	s_add_u32 s20, s20, s26
	s_addc_u32 s21, s21, 0
	global_load_dwordx4 v[56:59], v205, s[20:21] nt
	s_add_u32 s20, s20, s26
	s_addc_u32 s21, s21, 0
	global_load_dwordx4 v[60:63], v205, s[20:21] nt
	s_add_u32 s20, s20, s26
	s_addc_u32 s21, s21, 0
	global_load_dwordx4 v[64:67], v205, s[20:21] nt
	s_add_u32 s20, s20, s26
	s_addc_u32 s21, s21, 0
	global_load_dwordx4 v[68:71], v205, s[20:21] nt
	s_bitcmp1_b32 s27, 0
	s_cbranch_scc0 .Lw1d_nog_22
	s_load_dwordx16 s[80:95], s[24:25], 0x0
	s_load_dwordx16 s[48:63], s[24:25], 0x40
.Lw1d_nog_22:
	s_bitcmp1_b32 s27, 1
	s_cselect_b64 vcc, -1, 0
	s_lshr_b32 s0, s27, 8
	s_lshl_b32 s4, 1, s0
	v_cndmask_b32_e32 v207, v202, v203, vcc
	v_lshlrev_b32_e32 v206, s0, v207
	v_add_u32_e32 v206, v206, v204
	s_waitcnt vmcnt(0)
	s_bitcmp1_b32 s27, 0
	s_cbranch_scc0 .Lw1d_nomul_22
	s_waitcnt lgkmcnt(0)
	s_mov_b32 exec_hi, 0
	v_mul_f32_e32 v8, s80, v8
	v_mul_f32_e32 v9, s80, v9
	v_mul_f32_e32 v10, s80, v10
	v_mul_f32_e32 v11, s80, v11
	v_mul_f32_e32 v12, s81, v12
	v_mul_f32_e32 v13, s81, v13
	v_mul_f32_e32 v14, s81, v14
	v_mul_f32_e32 v15, s81, v15
	v_mul_f32_e32 v16, s82, v16
	v_mul_f32_e32 v17, s82, v17
	v_mul_f32_e32 v18, s82, v18
	v_mul_f32_e32 v19, s82, v19
	v_mul_f32_e32 v20, s83, v20
	v_mul_f32_e32 v21, s83, v21
	v_mul_f32_e32 v22, s83, v22
	v_mul_f32_e32 v23, s83, v23
	v_mul_f32_e32 v24, s84, v24
	v_mul_f32_e32 v25, s84, v25
	v_mul_f32_e32 v26, s84, v26
	v_mul_f32_e32 v27, s84, v27
	v_mul_f32_e32 v28, s85, v28
	v_mul_f32_e32 v29, s85, v29
	v_mul_f32_e32 v30, s85, v30
	v_mul_f32_e32 v31, s85, v31
	v_mul_f32_e32 v32, s86, v32
	v_mul_f32_e32 v33, s86, v33
	v_mul_f32_e32 v34, s86, v34
	v_mul_f32_e32 v35, s86, v35
	v_mul_f32_e32 v36, s87, v36
	v_mul_f32_e32 v37, s87, v37
	v_mul_f32_e32 v38, s87, v38
	v_mul_f32_e32 v39, s87, v39
	v_mul_f32_e32 v40, s88, v40
	v_mul_f32_e32 v41, s88, v41
	v_mul_f32_e32 v42, s88, v42
	v_mul_f32_e32 v43, s88, v43
	v_mul_f32_e32 v44, s89, v44
	v_mul_f32_e32 v45, s89, v45
	v_mul_f32_e32 v46, s89, v46
	v_mul_f32_e32 v47, s89, v47
	v_mul_f32_e32 v48, s90, v48
	v_mul_f32_e32 v49, s90, v49
	v_mul_f32_e32 v50, s90, v50
	v_mul_f32_e32 v51, s90, v51
	v_mul_f32_e32 v52, s91, v52
	v_mul_f32_e32 v53, s91, v53
	v_mul_f32_e32 v54, s91, v54
	v_mul_f32_e32 v55, s91, v55
	v_mul_f32_e32 v56, s92, v56
	v_mul_f32_e32 v57, s92, v57
	v_mul_f32_e32 v58, s92, v58
	v_mul_f32_e32 v59, s92, v59
	v_mul_f32_e32 v60, s93, v60
	v_mul_f32_e32 v61, s93, v61
	v_mul_f32_e32 v62, s93, v62
	v_mul_f32_e32 v63, s93, v63
	v_mul_f32_e32 v64, s94, v64
	v_mul_f32_e32 v65, s94, v65
	v_mul_f32_e32 v66, s94, v66
	v_mul_f32_e32 v67, s94, v67
	v_mul_f32_e32 v68, s95, v68
	v_mul_f32_e32 v69, s95, v69
	v_mul_f32_e32 v70, s95, v70
	v_mul_f32_e32 v71, s95, v71
	s_mov_b32 exec_lo, 0
	s_mov_b32 exec_hi, -1
	v_mul_f32_e32 v8, s48, v8
	v_mul_f32_e32 v9, s48, v9
	v_mul_f32_e32 v10, s48, v10
	v_mul_f32_e32 v11, s48, v11
	v_mul_f32_e32 v12, s49, v12
	v_mul_f32_e32 v13, s49, v13
	v_mul_f32_e32 v14, s49, v14
	v_mul_f32_e32 v15, s49, v15
	v_mul_f32_e32 v16, s50, v16
	v_mul_f32_e32 v17, s50, v17
	v_mul_f32_e32 v18, s50, v18
	v_mul_f32_e32 v19, s50, v19
	v_mul_f32_e32 v20, s51, v20
	v_mul_f32_e32 v21, s51, v21
	v_mul_f32_e32 v22, s51, v22
	v_mul_f32_e32 v23, s51, v23
	v_mul_f32_e32 v24, s52, v24
	v_mul_f32_e32 v25, s52, v25
	v_mul_f32_e32 v26, s52, v26
	v_mul_f32_e32 v27, s52, v27
	v_mul_f32_e32 v28, s53, v28
	v_mul_f32_e32 v29, s53, v29
	v_mul_f32_e32 v30, s53, v30
	v_mul_f32_e32 v31, s53, v31
	v_mul_f32_e32 v32, s54, v32
	v_mul_f32_e32 v33, s54, v33
	v_mul_f32_e32 v34, s54, v34
	v_mul_f32_e32 v35, s54, v35
	v_mul_f32_e32 v36, s55, v36
	v_mul_f32_e32 v37, s55, v37
	v_mul_f32_e32 v38, s55, v38
	v_mul_f32_e32 v39, s55, v39
	v_mul_f32_e32 v40, s56, v40
	v_mul_f32_e32 v41, s56, v41
	v_mul_f32_e32 v42, s56, v42
	v_mul_f32_e32 v43, s56, v43
	v_mul_f32_e32 v44, s57, v44
	v_mul_f32_e32 v45, s57, v45
	v_mul_f32_e32 v46, s57, v46
	v_mul_f32_e32 v47, s57, v47
	v_mul_f32_e32 v48, s58, v48
	v_mul_f32_e32 v49, s58, v49
	v_mul_f32_e32 v50, s58, v50
	v_mul_f32_e32 v51, s58, v51
	v_mul_f32_e32 v52, s59, v52
	v_mul_f32_e32 v53, s59, v53
	v_mul_f32_e32 v54, s59, v54
	v_mul_f32_e32 v55, s59, v55
	v_mul_f32_e32 v56, s60, v56
	v_mul_f32_e32 v57, s60, v57
	v_mul_f32_e32 v58, s60, v58
	v_mul_f32_e32 v59, s60, v59
	v_mul_f32_e32 v60, s61, v60
	v_mul_f32_e32 v61, s61, v61
	v_mul_f32_e32 v62, s61, v62
	v_mul_f32_e32 v63, s61, v63
	v_mul_f32_e32 v64, s62, v64
	v_mul_f32_e32 v65, s62, v65
	v_mul_f32_e32 v66, s62, v66
	v_mul_f32_e32 v67, s62, v67
	v_mul_f32_e32 v68, s63, v68
	v_mul_f32_e32 v69, s63, v69
	v_mul_f32_e32 v70, s63, v70
	v_mul_f32_e32 v71, s63, v71
	s_mov_b64 exec, -1
.Lw1d_nomul_22:
	v_cvt_pk_bf16_f32 v236, v8, v12
	v_cvt_pk_bf16_f32 v237, v16, v20
	v_cvt_pk_bf16_f32 v238, v24, v28
	v_cvt_pk_bf16_f32 v239, v32, v36
	global_store_dwordx4 v206, v[236:239], s[22:23]
	v_cvt_pk_bf16_f32 v240, v40, v44
	v_cvt_pk_bf16_f32 v241, v48, v52
	v_cvt_pk_bf16_f32 v242, v56, v60
	v_cvt_pk_bf16_f32 v243, v64, v68
	global_store_dwordx4 v206, v[240:243], s[22:23] offset:16
	s_add_u32 s22, s22, s4
	s_addc_u32 s23, s23, 0
	v_cvt_pk_bf16_f32 v244, v9, v13
	v_cvt_pk_bf16_f32 v245, v17, v21
	v_cvt_pk_bf16_f32 v246, v25, v29
	v_cvt_pk_bf16_f32 v247, v33, v37
	global_store_dwordx4 v206, v[244:247], s[22:23]
	v_cvt_pk_bf16_f32 v248, v41, v45
	v_cvt_pk_bf16_f32 v249, v49, v53
	v_cvt_pk_bf16_f32 v250, v57, v61
	v_cvt_pk_bf16_f32 v251, v65, v69
	global_store_dwordx4 v206, v[248:251], s[22:23] offset:16
	s_add_u32 s22, s22, s4
	s_addc_u32 s23, s23, 0
	v_cvt_pk_bf16_f32 v236, v10, v14
	v_cvt_pk_bf16_f32 v237, v18, v22
	v_cvt_pk_bf16_f32 v238, v26, v30
	v_cvt_pk_bf16_f32 v239, v34, v38
	global_store_dwordx4 v206, v[236:239], s[22:23]
	v_cvt_pk_bf16_f32 v240, v42, v46
	v_cvt_pk_bf16_f32 v241, v50, v54
	v_cvt_pk_bf16_f32 v242, v58, v62
	v_cvt_pk_bf16_f32 v243, v66, v70
	global_store_dwordx4 v206, v[240:243], s[22:23] offset:16
	s_add_u32 s22, s22, s4
	s_addc_u32 s23, s23, 0
	v_cvt_pk_bf16_f32 v244, v11, v15
	v_cvt_pk_bf16_f32 v245, v19, v23
	v_cvt_pk_bf16_f32 v246, v27, v31
	v_cvt_pk_bf16_f32 v247, v35, v39
	global_store_dwordx4 v206, v[244:247], s[22:23]
	v_cvt_pk_bf16_f32 v248, v43, v47
	v_cvt_pk_bf16_f32 v249, v51, v55
	v_cvt_pk_bf16_f32 v250, v59, v63
	v_cvt_pk_bf16_f32 v251, v67, v71
	global_store_dwordx4 v206, v[248:251], s[22:23] offset:16
	v_readlane_b32 s8, v254, 0
	v_readlane_b32 s9, v254, 1
	v_readlane_b32 s10, v254, 2
	v_readlane_b32 s11, v254, 3
	v_readlane_b32 s12, v254, 4
	v_readlane_b32 s13, v254, 5
	v_readlane_b32 s14, v254, 6
	v_readlane_b32 s15, v254, 7
	v_readlane_b32 s16, v254, 8
	v_readlane_b32 s17, v254, 9
	v_readlane_b32 s18, v254, 10
	v_readlane_b32 s19, v254, 11
	v_readlane_b32 s20, v254, 12
	v_readlane_b32 s21, v254, 13
	v_readlane_b32 s22, v254, 14
	v_readlane_b32 s23, v254, 15
	v_readlane_b32 s24, v254, 16
	v_readlane_b32 s25, v254, 17
	v_readlane_b32 s26, v254, 18
	v_readlane_b32 s27, v254, 19
	v_readlane_b32 s28, v254, 20
	v_readlane_b32 s29, v254, 21
	v_readlane_b32 s30, v254, 22
	v_readlane_b32 s31, v254, 23
	v_readlane_b32 s32, v254, 24
	v_readlane_b32 s33, v254, 25
	v_readlane_b32 s34, v254, 26
	v_readlane_b32 s35, v254, 27
	v_readlane_b32 s40, v254, 28
	v_readlane_b32 s41, v254, 29
	v_readlane_b32 s42, v254, 30
	v_readlane_b32 s43, v254, 31
	v_readlane_b32 s44, v254, 32
	v_readlane_b32 s45, v254, 33
	v_readlane_b32 s46, v254, 34
	v_readlane_b32 s47, v254, 35
	v_readlane_b32 s48, v254, 36
	v_readlane_b32 s49, v254, 37
	v_readlane_b32 s50, v254, 38
	v_readlane_b32 s51, v254, 39
	v_readlane_b32 s52, v254, 40
	v_readlane_b32 s53, v254, 41
	v_readlane_b32 s54, v254, 42
	v_readlane_b32 s55, v254, 43
	v_readlane_b32 s56, v254, 44
	v_readlane_b32 s57, v254, 45
	v_readlane_b32 s58, v254, 46
	v_readlane_b32 s59, v254, 47
	v_readlane_b32 s60, v254, 48
	v_readlane_b32 s61, v254, 49
	v_readlane_b32 s62, v254, 50
	v_readlane_b32 s63, v254, 51
	v_readlane_b32 s66, v254, 52
	v_readlane_b32 s67, v254, 53
	v_readlane_b32 s68, v254, 54
	v_readlane_b32 s69, v254, 55
	v_readlane_b32 s70, v254, 56
	v_readlane_b32 s71, v254, 57
	v_readlane_b32 s72, v254, 58
	v_readlane_b32 s73, v254, 59
	v_readlane_b32 s74, v254, 60
	v_readlane_b32 s75, v254, 61
	v_readlane_b32 s76, v254, 62
	v_readlane_b32 s77, v254, 63
	v_readlane_b32 s80, v255, 0
	v_readlane_b32 s81, v255, 1
	v_readlane_b32 s82, v255, 2
	v_readlane_b32 s83, v255, 3
	v_readlane_b32 s84, v255, 4
	v_readlane_b32 s85, v255, 5
	v_readlane_b32 s86, v255, 6
	v_readlane_b32 s87, v255, 7
	v_readlane_b32 s88, v255, 8
	v_readlane_b32 s89, v255, 9
	v_readlane_b32 s90, v255, 10
	v_readlane_b32 s91, v255, 11
	v_readlane_b32 s92, v255, 12
	v_readlane_b32 s93, v255, 13
	v_readlane_b32 s94, v255, 14
	v_readlane_b32 s95, v255, 15
	v_readlane_b32 s4, v255, 16
	v_readlane_b32 s5, v255, 17
	v_readlane_b32 s0, v255, 18
	v_readlane_b32 s1, v255, 19
